# nsa top-k rank loop rewritten with 64-bit (score, index) keys
# speedup vs baseline: 1.0313x; 1.0028x over previous
; DI void nsa_item(const Params& p, int b, int g, int qb, char* smem, int tid) {
;     ...
;     const int q = tid >> 4, sub = tid & 15;
;     float v[8];
; #pragma unroll
;     for (int jj = 0; jj < 8; ++jj) {
;       int n = sub + 16 * jj;
;       float x = imp[q * 132 + n];
;       bool forced = (n == 0) | (n == cur) | (n == cur - 1);
;       x = (n <= cur) ? (forced ? 1e4f : x) : -1e30f;
;       v[jj] = x; imp[q * 132 + n] = x;
;     }
;     __syncthreads();
;     int rk[8];
; #pragma unroll
;     for (int jj = 0; jj < 8; ++jj) rk[jj] = 0;
;     for (int n2 = 0; n2 <= cur; ++n2) {
;       float y = imp[q * 132 + n2];
; #pragma unroll
;       for (int jj = 0; jj < 8; ++jj) {
;         int n = sub + 16 * jj;
;         rk[jj] += ((y > v[jj]) | ((y == v[jj]) & (n2 < n))) ? 1 : 0;
;       }
;     }
.LBB0_784:
	s_lshr_b32 s2, s85, 6
	v_mul_lo_u32 v73, v89, s84
	s_add_i32 s0, s2, -1
	v_add_u32_e32 v8, s76, v73
	v_cmp_eq_u32_e32 vcc, 0, v90
	v_cmp_eq_u32_e64 s[4:5], s2, v90
	v_lshl_add_u32 v9, v90, 2, v8
	s_or_b64 s[4:5], vcc, s[4:5]
	v_cmp_eq_u32_e32 vcc, s0, v90
	v_or_b32_e32 v7, 16, v90
	v_or_b32_e32 v6, 32, v90
	v_or_b32_e32 v5, 48, v90
	v_or_b32_e32 v4, 64, v90
	v_or_b32_e32 v3, 0x50, v90
	v_or_b32_e32 v2, 0x60, v90
	v_or_b32_e32 v1, 0x70, v90
	v_lshl_add_u32 v10, v7, 2, v8
	v_lshl_add_u32 v11, v6, 2, v8
	v_lshl_add_u32 v12, v5, 2, v8
	v_lshl_add_u32 v15, v4, 2, v8
	v_lshl_add_u32 v69, v3, 2, v8
	v_lshl_add_u32 v70, v2, 2, v8
	v_lshl_add_u32 v71, v1, 2, v8
	ds_read_b32 v13, v9
	ds_read_b32 v14, v10
	ds_read_b32 v16, v11
	ds_read_b32 v66, v12
	ds_read_b32 v67, v15
	ds_read_b32 v68, v69
	ds_read_b32 v72, v70
	ds_read_b32 v74, v71
	s_or_b64 vcc, vcc, s[4:5]
	s_waitcnt lgkmcnt(7)
	v_cndmask_b32_e32 v13, v13, v232, vcc
	v_cmp_ge_u32_e32 vcc, s2, v90
	v_cmp_eq_u32_e64 s[4:5], s0, v7
	v_mov_b32_e32 v0, 0
	v_cndmask_b32_e32 v13, v231, v13, vcc
	v_cmp_eq_u32_e32 vcc, s2, v7
	s_or_b64 vcc, s[4:5], vcc
	ds_write_b32 v9, v13
	s_waitcnt lgkmcnt(7)
	v_cndmask_b32_e32 v9, v14, v232, vcc
	v_cmp_ge_u32_e32 vcc, s2, v7
	v_cmp_eq_u32_e64 s[4:5], s0, v6
	s_nop 0
	v_cndmask_b32_e32 v14, v231, v9, vcc
	v_cmp_eq_u32_e32 vcc, s2, v6
	s_or_b64 vcc, s[4:5], vcc
	v_cmp_eq_u32_e64 s[4:5], s0, v5
	s_waitcnt lgkmcnt(6)
	v_cndmask_b32_e32 v9, v16, v232, vcc
	v_cmp_ge_u32_e32 vcc, s2, v6
	ds_write_b32 v10, v14
	v_mov_b32_e32 v10, 0
	v_cndmask_b32_e32 v16, v231, v9, vcc
	v_cmp_eq_u32_e32 vcc, s2, v5
	s_or_b64 vcc, s[4:5], vcc
	v_cmp_eq_u32_e64 s[4:5], s0, v4
	s_waitcnt lgkmcnt(6)
	v_cndmask_b32_e32 v9, v66, v232, vcc
	v_cmp_ge_u32_e32 vcc, s2, v5
	ds_write_b32 v11, v16
	v_mov_b32_e32 v11, 0
	v_cndmask_b32_e32 v66, v231, v9, vcc
	v_cmp_eq_u32_e32 vcc, s2, v4
	s_or_b64 vcc, s[4:5], vcc
	v_cmp_eq_u32_e64 s[4:5], s0, v3
	s_waitcnt lgkmcnt(6)
	v_cndmask_b32_e32 v9, v67, v232, vcc
	v_cmp_ge_u32_e32 vcc, s2, v4
	ds_write_b32 v12, v66
	v_mov_b32_e32 v12, 0
	v_cndmask_b32_e32 v67, v231, v9, vcc
	v_cmp_eq_u32_e32 vcc, s2, v3
	s_or_b64 vcc, s[4:5], vcc
	v_cmp_eq_u32_e64 s[4:5], s0, v2
	s_waitcnt lgkmcnt(6)
	v_cndmask_b32_e32 v9, v68, v232, vcc
	v_cmp_ge_u32_e32 vcc, s2, v3
	ds_write_b32 v15, v67
	v_mov_b32_e32 v15, 0
	v_cndmask_b32_e32 v68, v231, v9, vcc
	v_cmp_eq_u32_e32 vcc, s2, v2
	s_or_b64 vcc, s[4:5], vcc
	ds_write_b32 v69, v68
	s_waitcnt lgkmcnt(7)
	v_cndmask_b32_e32 v9, v72, v232, vcc
	v_cmp_ge_u32_e32 vcc, s2, v2
	v_cmp_eq_u32_e64 s[4:5], s0, v1
	s_mov_b32 s0, 0
	v_cndmask_b32_e32 v69, v231, v9, vcc
	v_cmp_eq_u32_e32 vcc, s2, v1
	s_or_b64 vcc, s[4:5], vcc
	ds_write_b32 v70, v69
	s_waitcnt lgkmcnt(7)
	v_cndmask_b32_e32 v9, v74, v232, vcc
	v_cmp_ge_u32_e32 vcc, s2, v1
	s_cmp_gt_u32 s85, 63
	s_cselect_b64 s[8:9], -1, 0
	v_cndmask_b32_e32 v70, v231, v9, vcc
	ds_write_b32 v71, v70
	s_cmp_lt_u32 s85, 64
	v_mov_b32_e32 v9, 0
	v_mov_b32_e32 v71, 0
	v_mov_b32_e32 v72, 0
	s_waitcnt lgkmcnt(0)
	s_barrier
	s_cbranch_scc1 .LBB0_788
	v_writelane_b32 v255, s8, 28
	s_add_i32 s0, s2, 1
	s_and_b32 s3, s0, 0x7fffffe
	v_writelane_b32 v255, s9, 29
	v_writelane_b32 v255, s25, 30
	v_writelane_b32 v255, s24, 31
	v_writelane_b32 v255, s23, 32
	v_writelane_b32 v255, s22, 33
	v_writelane_b32 v255, s85, 34
	v_mov_b32_e32 v72, 0
	v_readlane_b32 s0, v255, 8
	v_mov_b32_e32 v71, 0
	v_mov_b32_e32 v15, 0
	v_add_u32_e32 v73, s0, v73
	s_mov_b32 s0, 0
	v_mov_b32_e32 v12, 0
	v_mov_b32_e32 v11, 0
	v_mov_b32_e32 v10, 0
	v_mov_b32_e32 v9, 0
	v_mov_b32_e32 v0, 0
	v_sub_u32_e32 v132, 0xff, v90
	v_mov_b32_e32 v133, v13
	v_sub_u32_e32 v134, 0xff, v7
	v_mov_b32_e32 v135, v14
	v_sub_u32_e32 v136, 0xff, v6
	v_mov_b32_e32 v137, v16
	v_sub_u32_e32 v138, 0xff, v5
	v_mov_b32_e32 v139, v66
	v_sub_u32_e32 v140, 0xff, v4
	v_mov_b32_e32 v141, v67
	v_sub_u32_e32 v142, 0xff, v3
	v_mov_b32_e32 v143, v68
	v_sub_u32_e32 v144, 0xff, v2
	v_mov_b32_e32 v145, v69
	v_sub_u32_e32 v146, 0xff, v1
	v_mov_b32_e32 v147, v70
.LBB0_786:
	v_add_u32_e32 v74, -4, v73
	ds_read_b64 v[74:75], v74
	s_sub_i32 s38, 0xff, s0
	v_mov_b32_e32 v76, s38
	s_add_i32 s38, s38, -1
	v_mov_b32_e32 v78, s38
	v_add_u32_e32 v73, 8, v73
	s_add_i32 s0, s0, 2
	s_waitcnt lgkmcnt(0)
	v_max_i32_e32 v77, 0, v74
	v_max_i32_e32 v79, 0, v75
	v_cmp_gt_u64_e64 s[6:7], v[76:77], v[132:133]
	v_cmp_gt_u64_e64 s[8:9], v[78:79], v[132:133]
	v_cmp_gt_u64_e64 s[10:11], v[76:77], v[134:135]
	v_cmp_gt_u64_e64 s[12:13], v[78:79], v[134:135]
	v_cmp_gt_u64_e64 s[14:15], v[76:77], v[136:137]
	v_cmp_gt_u64_e64 s[16:17], v[78:79], v[136:137]
	v_cmp_gt_u64_e64 s[18:19], v[76:77], v[138:139]
	v_cmp_gt_u64_e64 s[20:21], v[78:79], v[138:139]
	v_cmp_gt_u64_e64 s[22:23], v[76:77], v[140:141]
	v_cmp_gt_u64_e64 s[24:25], v[78:79], v[140:141]
	v_cmp_gt_u64_e64 s[26:27], v[76:77], v[142:143]
	v_cmp_gt_u64_e64 s[28:29], v[78:79], v[142:143]
	v_cmp_gt_u64_e64 s[30:31], v[76:77], v[144:145]
	v_cmp_gt_u64_e64 s[34:35], v[78:79], v[144:145]
	v_cmp_gt_u64_e64 s[36:37], v[76:77], v[146:147]
	v_cmp_gt_u64_e64 s[42:43], v[78:79], v[146:147]
	v_addc_co_u32_e64 v72, s[4:5], v72, 0, s[6:7]
	v_addc_co_u32_e64 v72, s[4:5], v72, 0, s[8:9]
	v_addc_co_u32_e64 v71, s[4:5], v71, 0, s[10:11]
	v_addc_co_u32_e64 v71, s[4:5], v71, 0, s[12:13]
	v_addc_co_u32_e64 v15, s[4:5], v15, 0, s[14:15]
	v_addc_co_u32_e64 v15, s[4:5], v15, 0, s[16:17]
	v_addc_co_u32_e64 v12, s[4:5], v12, 0, s[18:19]
	v_addc_co_u32_e64 v12, s[4:5], v12, 0, s[20:21]
	v_addc_co_u32_e64 v11, s[4:5], v11, 0, s[22:23]
	v_addc_co_u32_e64 v11, s[4:5], v11, 0, s[24:25]
	v_addc_co_u32_e64 v10, s[4:5], v10, 0, s[26:27]
	v_addc_co_u32_e64 v10, s[4:5], v10, 0, s[28:29]
	v_addc_co_u32_e64 v9, s[4:5], v9, 0, s[30:31]
	v_addc_co_u32_e64 v9, s[4:5], v9, 0, s[34:35]
	v_addc_co_u32_e64 v0, s[4:5], v0, 0, s[36:37]
	v_addc_co_u32_e64 v0, s[4:5], v0, 0, s[42:43]
	s_cmp_eq_u32 s0, s3
	s_cbranch_scc0 .LBB0_786
	v_readlane_b32 s92, v255, 10
	v_readlane_b32 s93, v255, 11
	s_load_dword s91, s[92:93], 0x190
	v_readlane_b32 s94, v255, 12
	v_readlane_b32 s60, v255, 14
	v_readlane_b32 s64, v255, 18
	v_readlane_b32 s8, v255, 28
	v_readlane_b32 s90, v255, 9
	v_readlane_b32 s95, v255, 13
	v_readlane_b32 s61, v255, 15
	v_readlane_b32 s62, v255, 16
	v_readlane_b32 s63, v255, 17
	v_readlane_b32 s65, v255, 19
	v_readlane_b32 s66, v255, 20
	v_readlane_b32 s67, v255, 21
	v_readlane_b32 s68, v255, 22
	v_readlane_b32 s69, v255, 23
	v_readlane_b32 s70, v255, 24
	v_readlane_b32 s71, v255, 25
	v_readlane_b32 s72, v255, 26
	s_movk_i32 s73, 0x7ff
	s_movk_i32 s74, 0x60
	s_movk_i32 s75, 0x1080
	v_readlane_b32 s76, v255, 27
	s_movk_i32 s77, 0xe7f
	s_movk_i32 s78, 0x80
	s_movk_i32 s79, 0xf0
	s_movk_i32 s80, 0x70
	s_mov_b64 s[82:83], 0x80
	s_mov_b32 s81, 0x10000
	s_movk_i32 s84, 0x210
	v_readlane_b32 s85, v255, 34
	v_readlane_b32 s22, v255, 33
	v_readlane_b32 s23, v255, 32
	v_readlane_b32 s24, v255, 31
	v_readlane_b32 s25, v255, 30
	v_readlane_b32 s9, v255, 29
